# full grid barrier at the DN2(layer 0)->CONV(layer 1) seam without the L2 write-back (ordering-only seam)
# baseline (speedup 1.0000x reference)
.LBB0_1423:
	s_andn2_saveexec_b64 s[0:1], s[0:1]
	s_cbranch_execz .LBB0_1441
	s_mov_b64 s[0:1], exec
	s_cmp_eq_u32 s71, 9
	s_cbranch_scc1 .Lno_wbl2
	buffer_wbl2 sc1
.Lno_wbl2:
	s_waitcnt lgkmcnt(0)
	s_waitcnt vmcnt(0)
	v_mbcnt_lo_u32_b32 v0, s0, 0
	v_mbcnt_hi_u32_b32 v0, s1, v0
	v_cmp_eq_u32_e32 vcc, 0, v0
	s_and_saveexec_b64 s[12:13], vcc
	s_cbranch_execz .LBB0_1426
	s_bcnt1_i32_b64 s0, s[0:1]
	v_mov_b32_e32 v3, s0
	v_readlane_b32 s0, v253, 35
	v_readlane_b32 s1, v253, 36
	s_nop 4
	global_atomic_add v3, v1, v3, s[0:1] sc0
